# class split thresholds 41,33,30,30
# baseline (speedup 1.0000x reference)
.Lqa_prompt:
	s_add_i32 s63, s26, -4
	s_and_b32 s64, s62, 1
	s_lshr_b32 s65, s62, 1
	s_mov_b32 s67, 0
	s_movk_i32 s66, 41
	s_sub_i32 s59, 64, s66
	s_cmp_eq_u32 s64, 0
	s_cselect_b32 s59, s59, s66
	s_cmp_lt_u32 s63, s59
	s_cbranch_scc1 .Lqa_found
	s_sub_i32 s63, s63, s59
	s_addk_i32 s67, 0x100
	s_movk_i32 s66, 33
	s_sub_i32 s59, 64, s66
	s_cmp_eq_u32 s64, 0
	s_cselect_b32 s59, s59, s66
	s_cmp_lt_u32 s63, s59
	s_cbranch_scc1 .Lqa_found
	s_sub_i32 s63, s63, s59
	s_addk_i32 s67, 0x100
	s_movk_i32 s66, 30
	s_sub_i32 s59, 64, s66
	s_cmp_eq_u32 s64, 0
	s_cselect_b32 s59, s59, s66
	s_cmp_lt_u32 s63, s59
	s_cbranch_scc1 .Lqa_found
	s_sub_i32 s63, s63, s59
	s_addk_i32 s67, 0x100
	s_movk_i32 s66, 30
	s_sub_i32 s59, 64, s66
	s_cmp_eq_u32 s64, 0
	s_cselect_b32 s59, s59, s66
	s_cmp_lt_u32 s63, s59
	s_cbranch_scc1 .Lqa_found
	s_sub_i32 s63, s63, s59
	s_addk_i32 s67, 0x100
	s_cmp_lt_u32 s63, 0x41
	s_cbranch_scc1 .Lqa_lru
	s_sub_i32 s63, s63, 0x41
	s_add_i32 s98, s98, 1
	s_cmp_ge_u32 s98, 8
	s_cbranch_scc1 .LBB0_1418
	s_add_i32 s62, s80, s98
	s_and_b32 s62, s62, 7
	s_lshl_b32 s63, s62, 6
	s_add_u32 s8, s86, 0x1e28f900
	s_addc_u32 s9, s87, 0
	s_add_u32 s8, s8, s63
	s_addc_u32 s9, s9, 0
	s_barrier
	s_and_saveexec_b64 s[0:1], s[82:83]
	s_cbranch_execz .Lqa_nodraw
	v_mov_b32_e32 v2, 0
	v_mov_b32_e32 v3, 1
	s_nop 1
	global_atomic_add v3, v2, v3, s[8:9] sc0
	s_waitcnt vmcnt(0)
	v_mov_b32_e32 v2, s3
	ds_write_b32 v2, v3
